# attention prep: sum-of-squares reduction uses DPP row rotates for the xor 8/4/2/1 steps (same partners and order), one ds_bpermute kept for xor 16
# baseline (speedup 1.0000x reference)
; __device__ __forceinline__ unsigned cvt_pk_bf16(float lo, float hi) { unsigned r; asm volatile("v_cvt_pk_bf16_f32 %0, %1, %2" : "=v"(r) : "v"(lo), "v"(hi)); return r; }
; __device__ __forceinline__ float bf_lo(unsigned v) { return __uint_as_float(v << 16); }
; __device__ __forceinline__ float bf_hi(unsigned v) { return __uint_as_float(v & 0xffff0000u); }
; __device__ __forceinline__ void prep_phase(const int TID, const int BID, PP p) {
;     ...
;         const bf16_t* r = raw + (size_t)tok * NINP; const int pos = tok & 4095;
;         float cq[4], sq[4], ci[4], si[4];
;         { const int j = lane & 3, ji = lane & 1;
; #pragma unroll
;           for (int e = 0; e < 4; ++e) {
;               rope_cs(pos, exp2f(-(float)(4 * j + e) * (L2T / 16.0f)), cq[e], sq[e]);
;               rope_cs(pos, exp2f(-(float)(4 * ji + e) * (L2T / 8.0f)), ci[e], si[e]); } }
; #pragma unroll
;         for (int it = 0; it < 10; ++it) {
;             const int head = 2 * it + (lane >> 5), j = lane & 31;
;             const bool isq = head < 16;
;             const int col = isq ? head * 128 : 2048 + (head - 16) * 128;
;             const u32x2 rw = *(const u32x2*)(r + col + 4 * j);
;             f32x4 v = (f32x4){bf_lo(rw.x), bf_hi(rw.x), bf_lo(rw.y), bf_hi(rw.y)};
;             float ss = v[0] * v[0] + v[1] * v[1] + v[2] * v[2] + v[3] * v[3];
; #pragma unroll
;             for (int o = 16; o > 0; o >>= 1) ss += __shfl_xor(ss, o);
;             const float rn = rinv_of(ss, 1.0f / 128.0f);
;             const f32x4 g4 = *(const f32x4*)((isq ? p->attn_q_gain : p->attn_k_gain) + 4 * j);
;             v = v * rn * g4;
;             f32x4 pt;
; #pragma unroll
;             for (int e = 0; e < 4; ++e) pt[e] = __shfl_xor(v[e], 4);
;             if (j < 8) {
; #pragma unroll
;                 for (int e = 0; e < 4; ++e) v[e] = (j < 4) ? v[e] * cq[e] - pt[e] * sq[e] : v[e] * cq[e] + pt[e] * sq[e];
;             }
;             u32x2 o; o.x = cvt_pk_bf16(v[0], v[1]); o.y = cvt_pk_bf16(v[2], v[3]);
;             { int w8 = __builtin_amdgcn_cvt_pk_fp8_f32(v[0], v[1], 0, false); w8 = __builtin_amdgcn_cvt_pk_fp8_f32(v[2], v[3], w8, true);
;               if (isq) *(int*)((unsigned char*)Qb + (size_t)tok * 2048 + head * 128 + 4 * j) = w8;
;               else *(int*)((unsigned char*)Kb + (size_t)tok * 512 + (head - 16) * 128 + 4 * j) = w8; }
.LBB0_748:
	v_and_b32_e32 v40, 0xfff, v62
	v_cvt_f64_u32_e32 v[40:41], v40
	s_mov_b32 s0, 0x6dc9c883
	v_mul_f64 v[42:43], v[0:1], v[40:41]
	s_mov_b32 s1, 0x3fc45f30
	v_mul_f64 v[44:45], v[42:43], s[0:1]
	v_rndne_f64_e32 v[44:45], v[44:45]
	v_fma_f64 v[42:43], v[42:43], s[0:1], -v[44:45]
	v_mul_f64 v[44:45], v[4:5], v[40:41]
	v_mul_f64 v[48:49], v[44:45], s[0:1]
	v_rndne_f64_e32 v[48:49], v[48:49]
	v_fma_f64 v[44:45], v[44:45], s[0:1], -v[48:49]
	v_cvt_f32_f64_e32 v42, v[42:43]
	v_cvt_f32_f64_e32 v43, v[44:45]
	v_mul_f64 v[44:45], v[8:9], v[40:41]
	v_mul_f64 v[50:51], v[12:13], v[40:41]
	v_mul_f64 v[48:49], v[44:45], s[0:1]
	s_waitcnt lgkmcnt(0)
	v_mul_f64 v[52:53], v[50:51], s[0:1]
	v_rndne_f64_e32 v[48:49], v[48:49]
	v_rndne_f64_e32 v[52:53], v[52:53]
	v_fma_f64 v[44:45], v[44:45], s[0:1], -v[48:49]
	v_fma_f64 v[50:51], v[50:51], s[0:1], -v[52:53]
	v_cvt_f32_f64_e32 v44, v[44:45]
	v_cvt_f32_f64_e32 v45, v[50:51]
	v_lshl_add_u64 v[50:51], s[2:3], 0, v[26:27]
	s_mov_b32 s0, 0x1b500000
	v_add_co_u32_e32 v54, vcc, s0, v50
	v_sin_f32_e32 v46, v42
	s_nop 0
	v_addc_co_u32_e32 v55, vcc, 0, v51, vcc
	global_load_dwordx2 v[56:57], v[54:55], off
	v_readlane_b32 s26, v254, 15
	v_readlane_b32 s27, v254, 16
	v_mbcnt_lo_u32_b32 v216, -1, 0
	v_mbcnt_hi_u32_b32 v216, -1, v216
	v_lshlrev_b32_e32 v216, 3, v216
	v_mov_b32_e32 v217, 0
	s_mov_b64 s[28:29], 0x2000
	v_lshl_add_u64 v[212:213], v[54:55], 0, s[26:27]
	v_lshl_add_u64 v[212:213], v[212:213], 0, v[216:217]
	v_lshl_add_u64 v[214:215], v[212:213], 0, s[28:29]
	global_load_dwordx4 v[208:211], v[212:213], off
	global_load_dwordx4 v[208:211], v[212:213], off offset:1024
	global_load_dwordx4 v[208:211], v[212:213], off offset:2048
	global_load_dwordx4 v[208:211], v[212:213], off offset:3072
	global_load_dwordx4 v[208:211], v[214:215], off offset:-4096
	global_load_dwordx4 v[208:211], v[214:215], off offset:-3072
	global_load_dwordx4 v[208:211], v[214:215], off offset:-2048
	global_load_dwordx4 v[208:211], v[214:215], off offset:-1024
	global_load_dwordx4 v[208:211], v[214:215], off
	v_cos_f32_e32 v42, v42
	v_sin_f32_e32 v47, v43
	v_cos_f32_e32 v43, v43
	v_sin_f32_e32 v48, v44
	v_cos_f32_e32 v44, v44
	v_sin_f32_e32 v49, v45
	v_cos_f32_e32 v45, v45
	s_waitcnt vmcnt(0)
	v_lshlrev_b32_e32 v60, 16, v56
	v_and_b32_e32 v61, 0xffff0000, v56
	v_and_b32_e32 v52, 0xffff0000, v57
	v_pk_mul_f32 v[58:59], v[60:61], v[60:61]
	v_and_b32_e32 v53, s0, v57
	v_lshlrev_b32_e32 v57, 16, v57
	v_mov_b32_e32 v56, v52
	v_pk_mul_f32 v[68:69], v[56:57], v[56:57]
	v_add_f32_e32 v58, v58, v59
	v_add_f32_e32 v58, v69, v58
	v_add_f32_e32 v58, v68, v58
	global_load_dwordx4 v[68:71], v[16:17], off
	ds_bpermute_b32 v59, v64, v58
	v_pk_mov_b32 v[52:53], v[56:57], v[52:53] op_sel:[1,0]
	s_waitcnt lgkmcnt(0)
	v_add_f32_e32 v58, v58, v59
	s_nop 1
	v_add_f32_dpp v58, v58, v58 row_ror:8 row_mask:0xf bank_mask:0xf
	s_nop 1
	v_add_f32_dpp v58, v58, v58 row_ror:4 row_mask:0xf bank_mask:0xf
	s_nop 1
	v_add_f32_dpp v58, v58, v58 row_ror:2 row_mask:0xf bank_mask:0xf
	s_nop 1
	v_add_f32_dpp v58, v58, v58 row_ror:1 row_mask:0xf bank_mask:0xf
	v_fmamk_f32 v58, v58, 0x3c000000, v189
	v_cmp_gt_f32_e32 vcc, s78, v58
	v_mul_f32_e32 v59, 0x4b800000, v58
	s_nop 0
	v_cndmask_b32_e32 v58, v58, v59, vcc
	v_rsq_f32_e32 v58, v58
	s_nop 0
	v_mul_f32_e32 v59, 0x45800000, v58
	v_cndmask_b32_e32 v58, v58, v59, vcc
	v_pk_mul_f32 v[60:61], v[58:59], v[60:61] op_sel_hi:[0,1]
	v_pk_mul_f32 v[52:53], v[58:59], v[52:53] op_sel_hi:[0,1]
	s_waitcnt vmcnt(0)
	v_pk_mul_f32 v[52:53], v[70:71], v[52:53]
	v_pk_mul_f32 v[56:57], v[68:69], v[60:61]
	ds_bpermute_b32 v60, v63, v56
	ds_bpermute_b32 v61, v63, v57
	ds_bpermute_b32 v58, v63, v52
	ds_bpermute_b32 v59, v63, v53
	s_and_saveexec_b64 s[22:23], s[8:9]
	s_cbranch_execz .LBB0_750
	s_waitcnt lgkmcnt(2)
	v_pk_mul_f32 v[60:61], v[46:47], v[60:61]
	s_waitcnt lgkmcnt(0)
	v_pk_mul_f32 v[58:59], v[48:49], v[58:59]
	v_cndmask_b32_e64 v61, v61, -v61, s[10:11]
	v_cndmask_b32_e64 v60, v60, -v60, s[10:11]
	v_cndmask_b32_e64 v59, v59, -v59, s[10:11]
	v_cndmask_b32_e64 v58, v58, -v58, s[10:11]
	v_pk_fma_f32 v[56:57], v[42:43], v[56:57], v[60:61]
	v_pk_fma_f32 v[52:53], v[44:45], v[52:53], v[58:59]
.LBB0_750:
	s_or_b64 exec, exec, s[22:23]
	s_waitcnt lgkmcnt(1)
	v_cvt_pk_bf16_f32 v58, v56, v57
	s_nop 0
	v_cvt_pk_bf16_f32 v58, v52, v53
	s_nop 0
	v_mov_b32_e32 v58, v161
	v_cvt_pk_fp8_f32 v58, v56, v57
	v_cvt_pk_fp8_f32 v58, v52, v53 op_sel:[0,0,1]
	v_lshl_add_u64 v[52:53], s[2:3], 0, v[38:39]
	global_store_dword v[52:53], v58, off offset:-1024
	s_waitcnt lgkmcnt(0)
	global_load_dwordx4 v[56:59], v[16:17], off
	s_nop 0
	global_load_dwordx2 v[54:55], v[54:55], off offset:512
	s_waitcnt vmcnt(0)
	v_lshlrev_b32_e32 v60, 16, v54
	v_and_b32_e32 v61, 0xffff0000, v54
	v_and_b32_e32 v70, 0xffff0000, v55
	v_pk_mul_f32 v[68:69], v[60:61], v[60:61]
	v_and_b32_e32 v71, s0, v55
	v_lshlrev_b32_e32 v55, 16, v55
	v_mov_b32_e32 v54, v70
	v_pk_mul_f32 v[72:73], v[54:55], v[54:55]
	v_add_f32_e32 v68, v68, v69
	v_add_f32_e32 v68, v73, v68
	v_add_f32_e32 v68, v72, v68
	ds_bpermute_b32 v69, v64, v68
	v_pk_mov_b32 v[54:55], v[54:55], v[70:71] op_sel:[1,0]
	s_waitcnt lgkmcnt(0)
	v_add_f32_e32 v68, v68, v69
	s_nop 1
	v_add_f32_dpp v68, v68, v68 row_ror:8 row_mask:0xf bank_mask:0xf
	s_nop 1
	v_add_f32_dpp v68, v68, v68 row_ror:4 row_mask:0xf bank_mask:0xf
	s_nop 1
	v_add_f32_dpp v68, v68, v68 row_ror:2 row_mask:0xf bank_mask:0xf
	s_nop 1
	v_add_f32_dpp v68, v68, v68 row_ror:1 row_mask:0xf bank_mask:0xf
	v_fmamk_f32 v68, v68, 0x3c000000, v189
	v_cmp_gt_f32_e32 vcc, s78, v68
	v_mul_f32_e32 v69, 0x4b800000, v68
	s_nop 0
	v_cndmask_b32_e32 v68, v68, v69, vcc
	v_rsq_f32_e32 v68, v68
	s_nop 0
	v_mul_f32_e32 v69, 0x45800000, v68
	v_cndmask_b32_e32 v68, v68, v69, vcc
	v_pk_mul_f32 v[60:61], v[68:69], v[60:61] op_sel_hi:[0,1]
	v_pk_mul_f32 v[54:55], v[68:69], v[54:55] op_sel_hi:[0,1]
	v_pk_mul_f32 v[54:55], v[58:59], v[54:55]
	v_pk_mul_f32 v[56:57], v[56:57], v[60:61]
	ds_bpermute_b32 v60, v63, v56
	ds_bpermute_b32 v61, v63, v57
	ds_bpermute_b32 v58, v63, v54
	ds_bpermute_b32 v59, v63, v55
	s_and_saveexec_b64 s[22:23], s[8:9]
	s_cbranch_execz .LBB0_752
	s_waitcnt lgkmcnt(2)
	v_pk_mul_f32 v[60:61], v[46:47], v[60:61]
	s_waitcnt lgkmcnt(0)
	v_pk_mul_f32 v[58:59], v[48:49], v[58:59]
	v_cndmask_b32_e64 v61, v61, -v61, s[10:11]
	v_cndmask_b32_e64 v60, v60, -v60, s[10:11]
	v_cndmask_b32_e64 v59, v59, -v59, s[10:11]
	v_cndmask_b32_e64 v58, v58, -v58, s[10:11]
	v_pk_fma_f32 v[56:57], v[42:43], v[56:57], v[60:61]
	v_pk_fma_f32 v[54:55], v[44:45], v[54:55], v[58:59]
; __device__ __forceinline__ unsigned cvt_pk_bf16(float lo, float hi) { unsigned r; asm volatile("v_cvt_pk_bf16_f32 %0, %1, %2" : "=v"(r) : "v"(lo), "v"(hi)); return r; }
; __device__ __forceinline__ float bf_lo(unsigned v) { return __uint_as_float(v << 16); }
; __device__ __forceinline__ float bf_hi(unsigned v) { return __uint_as_float(v & 0xffff0000u); }
; __device__ __forceinline__ float rinv_of(float ss, float invn) { return rsqrtf(ss * invn + 1e-6f); }
; __device__ __forceinline__ void prep_phase(const int TID, const int BID, PP p) {
;     ...
;         for (int it = 0; it < 10; ++it) {
;             const int head = 2 * it + (lane >> 5), j = lane & 31;
;             const bool isq = head < 16;
;             const int col = isq ? head * 128 : 2048 + (head - 16) * 128;
;             const u32x2 rw = *(const u32x2*)(r + col + 4 * j);
;             f32x4 v = (f32x4){bf_lo(rw.x), bf_hi(rw.x), bf_lo(rw.y), bf_hi(rw.y)};
;             float ss = v[0] * v[0] + v[1] * v[1] + v[2] * v[2] + v[3] * v[3];
; #pragma unroll
;             for (int o = 16; o > 0; o >>= 1) ss += __shfl_xor(ss, o);
;             const float rn = rinv_of(ss, 1.0f / 128.0f);
;             const f32x4 g4 = *(const f32x4*)((isq ? p->attn_q_gain : p->attn_k_gain) + 4 * j);
;             v = v * rn * g4;
;             f32x4 pt;
; #pragma unroll
;             for (int e = 0; e < 4; ++e) pt[e] = __shfl_xor(v[e], 4);
;             if (j < 8) {
; #pragma unroll
;                 for (int e = 0; e < 4; ++e) v[e] = (j < 4) ? v[e] * cq[e] - pt[e] * sq[e] : v[e] * cq[e] + pt[e] * sq[e];
;             }
;             u32x2 o; o.x = cvt_pk_bf16(v[0], v[1]); o.y = cvt_pk_bf16(v[2], v[3]);
;             { int w8 = __builtin_amdgcn_cvt_pk_fp8_f32(v[0], v[1], 0, false); w8 = __builtin_amdgcn_cvt_pk_fp8_f32(v[2], v[3], w8, true);
;               if (isq) *(int*)((unsigned char*)Qb + (size_t)tok * 2048 + head * 128 + 4 * j) = w8;
;               else *(int*)((unsigned char*)Kb + (size_t)tok * 512 + (head - 16) * 128 + 4 * j) = w8; }
.LBB0_752:
	s_or_b64 exec, exec, s[22:23]
	s_waitcnt lgkmcnt(1)
	v_cvt_pk_bf16_f32 v58, v56, v57
	s_nop 0
	v_cvt_pk_bf16_f32 v58, v54, v55
	s_nop 0
	v_mov_b32_e32 v58, v161
	v_cvt_pk_fp8_f32 v58, v56, v57
	v_cvt_pk_fp8_f32 v58, v54, v55 op_sel:[0,0,1]
	v_add_co_u32_e32 v54, vcc, 0x1b500000, v50
	global_store_dword v[52:53], v58, off offset:-768
	s_nop 0
	v_addc_co_u32_e32 v55, vcc, 0, v51, vcc
	global_load_dwordx2 v[54:55], v[54:55], off offset:1024
	s_waitcnt vmcnt(0)
	v_lshlrev_b32_e32 v60, 16, v54
	s_waitcnt lgkmcnt(0)
	global_load_dwordx4 v[56:59], v[16:17], off
	v_and_b32_e32 v61, 0xffff0000, v54
	v_and_b32_e32 v70, 0xffff0000, v55
	v_pk_mul_f32 v[68:69], v[60:61], v[60:61]
	v_and_b32_e32 v71, s0, v55
	v_lshlrev_b32_e32 v55, 16, v55
	v_mov_b32_e32 v54, v70
	v_pk_mul_f32 v[72:73], v[54:55], v[54:55]
	v_add_f32_e32 v68, v68, v69
	v_add_f32_e32 v68, v73, v68
	v_add_f32_e32 v68, v72, v68
	ds_bpermute_b32 v69, v64, v68
	v_pk_mov_b32 v[54:55], v[54:55], v[70:71] op_sel:[1,0]
	s_waitcnt lgkmcnt(0)
	v_add_f32_e32 v68, v68, v69
	s_nop 1
	v_add_f32_dpp v68, v68, v68 row_ror:8 row_mask:0xf bank_mask:0xf
	s_nop 1
	v_add_f32_dpp v68, v68, v68 row_ror:4 row_mask:0xf bank_mask:0xf
	s_nop 1
	v_add_f32_dpp v68, v68, v68 row_ror:2 row_mask:0xf bank_mask:0xf
	s_nop 1
	v_add_f32_dpp v68, v68, v68 row_ror:1 row_mask:0xf bank_mask:0xf
	v_fmamk_f32 v68, v68, 0x3c000000, v189
	v_cmp_gt_f32_e32 vcc, s78, v68
	v_mul_f32_e32 v69, 0x4b800000, v68
	s_nop 0
	v_cndmask_b32_e32 v68, v68, v69, vcc
	v_rsq_f32_e32 v68, v68
	s_nop 0
	v_mul_f32_e32 v69, 0x45800000, v68
	v_cndmask_b32_e32 v68, v68, v69, vcc
	v_pk_mul_f32 v[60:61], v[68:69], v[60:61] op_sel_hi:[0,1]
	v_pk_mul_f32 v[54:55], v[68:69], v[54:55] op_sel_hi:[0,1]
	s_waitcnt vmcnt(0)
	v_pk_mul_f32 v[54:55], v[58:59], v[54:55]
	v_pk_mul_f32 v[56:57], v[56:57], v[60:61]
	ds_bpermute_b32 v60, v63, v56
	ds_bpermute_b32 v61, v63, v57
	ds_bpermute_b32 v58, v63, v54
	ds_bpermute_b32 v59, v63, v55
	s_and_saveexec_b64 s[22:23], s[8:9]
	s_cbranch_execz .LBB0_754
	s_waitcnt lgkmcnt(2)
	v_pk_mul_f32 v[60:61], v[46:47], v[60:61]
	s_waitcnt lgkmcnt(0)
	v_pk_mul_f32 v[58:59], v[48:49], v[58:59]
	v_cndmask_b32_e64 v61, v61, -v61, s[10:11]
	v_cndmask_b32_e64 v60, v60, -v60, s[10:11]
	v_cndmask_b32_e64 v59, v59, -v59, s[10:11]
	v_cndmask_b32_e64 v58, v58, -v58, s[10:11]
	v_pk_fma_f32 v[56:57], v[42:43], v[56:57], v[60:61]
	v_pk_fma_f32 v[54:55], v[44:45], v[54:55], v[58:59]
.LBB0_754:
	s_or_b64 exec, exec, s[22:23]
	s_waitcnt lgkmcnt(1)
	v_cvt_pk_bf16_f32 v58, v56, v57
	s_nop 0
	v_cvt_pk_bf16_f32 v58, v54, v55
	s_nop 0
	v_mov_b32_e32 v58, v161
	v_cvt_pk_fp8_f32 v58, v56, v57
	v_cvt_pk_fp8_f32 v58, v54, v55 op_sel:[0,0,1]
	v_add_co_u32_e32 v54, vcc, 0x1b500000, v50
	global_store_dword v[52:53], v58, off offset:-512
	s_nop 0
	v_addc_co_u32_e32 v55, vcc, 0, v51, vcc
	global_load_dwordx2 v[54:55], v[54:55], off offset:1536
	s_waitcnt vmcnt(0)
	v_lshlrev_b32_e32 v60, 16, v54
	s_waitcnt lgkmcnt(0)
	global_load_dwordx4 v[56:59], v[16:17], off
	v_and_b32_e32 v61, 0xffff0000, v54
	v_and_b32_e32 v70, 0xffff0000, v55
	v_pk_mul_f32 v[68:69], v[60:61], v[60:61]
	v_and_b32_e32 v71, s0, v55
	v_lshlrev_b32_e32 v55, 16, v55
	v_mov_b32_e32 v54, v70
	v_pk_mul_f32 v[72:73], v[54:55], v[54:55]
	v_add_f32_e32 v68, v68, v69
	v_add_f32_e32 v68, v73, v68
	v_add_f32_e32 v68, v72, v68
	ds_bpermute_b32 v69, v64, v68
	v_pk_mov_b32 v[54:55], v[54:55], v[70:71] op_sel:[1,0]
	s_waitcnt lgkmcnt(0)
	v_add_f32_e32 v68, v68, v69
	s_nop 1
	v_add_f32_dpp v68, v68, v68 row_ror:8 row_mask:0xf bank_mask:0xf
	s_nop 1
	v_add_f32_dpp v68, v68, v68 row_ror:4 row_mask:0xf bank_mask:0xf
	s_nop 1
	v_add_f32_dpp v68, v68, v68 row_ror:2 row_mask:0xf bank_mask:0xf
	s_nop 1
	v_add_f32_dpp v68, v68, v68 row_ror:1 row_mask:0xf bank_mask:0xf
	v_fmamk_f32 v68, v68, 0x3c000000, v189
	v_cmp_gt_f32_e32 vcc, s78, v68
	v_mul_f32_e32 v69, 0x4b800000, v68
	s_nop 0
	v_cndmask_b32_e32 v68, v68, v69, vcc
	v_rsq_f32_e32 v68, v68
	s_nop 0
	v_mul_f32_e32 v69, 0x45800000, v68
	v_cndmask_b32_e32 v68, v68, v69, vcc
	v_pk_mul_f32 v[60:61], v[68:69], v[60:61] op_sel_hi:[0,1]
	v_pk_mul_f32 v[54:55], v[68:69], v[54:55] op_sel_hi:[0,1]
	s_waitcnt vmcnt(0)
	v_pk_mul_f32 v[54:55], v[58:59], v[54:55]
	v_pk_mul_f32 v[56:57], v[56:57], v[60:61]
	ds_bpermute_b32 v60, v63, v56
	ds_bpermute_b32 v61, v63, v57
	ds_bpermute_b32 v58, v63, v54
	ds_bpermute_b32 v59, v63, v55
	s_and_saveexec_b64 s[22:23], s[8:9]
	s_cbranch_execz .LBB0_756
	s_waitcnt lgkmcnt(2)
	v_pk_mul_f32 v[60:61], v[46:47], v[60:61]
	s_waitcnt lgkmcnt(0)
	v_pk_mul_f32 v[58:59], v[48:49], v[58:59]
	v_cndmask_b32_e64 v61, v61, -v61, s[10:11]
	v_cndmask_b32_e64 v60, v60, -v60, s[10:11]
	v_cndmask_b32_e64 v59, v59, -v59, s[10:11]
	v_cndmask_b32_e64 v58, v58, -v58, s[10:11]
	v_pk_fma_f32 v[56:57], v[42:43], v[56:57], v[60:61]
	v_pk_fma_f32 v[54:55], v[44:45], v[54:55], v[58:59]
; __device__ __forceinline__ unsigned cvt_pk_bf16(float lo, float hi) { unsigned r; asm volatile("v_cvt_pk_bf16_f32 %0, %1, %2" : "=v"(r) : "v"(lo), "v"(hi)); return r; }
; __device__ __forceinline__ float bf_lo(unsigned v) { return __uint_as_float(v << 16); }
; __device__ __forceinline__ float bf_hi(unsigned v) { return __uint_as_float(v & 0xffff0000u); }
; __device__ __forceinline__ float rinv_of(float ss, float invn) { return rsqrtf(ss * invn + 1e-6f); }
; __device__ __forceinline__ void prep_phase(const int TID, const int BID, PP p) {
;     ...
;         for (int it = 0; it < 10; ++it) {
;             const int head = 2 * it + (lane >> 5), j = lane & 31;
;             const bool isq = head < 16;
;             const int col = isq ? head * 128 : 2048 + (head - 16) * 128;
;             const u32x2 rw = *(const u32x2*)(r + col + 4 * j);
;             f32x4 v = (f32x4){bf_lo(rw.x), bf_hi(rw.x), bf_lo(rw.y), bf_hi(rw.y)};
;             float ss = v[0] * v[0] + v[1] * v[1] + v[2] * v[2] + v[3] * v[3];
; #pragma unroll
;             for (int o = 16; o > 0; o >>= 1) ss += __shfl_xor(ss, o);
;             const float rn = rinv_of(ss, 1.0f / 128.0f);
;             const f32x4 g4 = *(const f32x4*)((isq ? p->attn_q_gain : p->attn_k_gain) + 4 * j);
;             v = v * rn * g4;
;             f32x4 pt;
; #pragma unroll
;             for (int e = 0; e < 4; ++e) pt[e] = __shfl_xor(v[e], 4);
;             if (j < 8) {
; #pragma unroll
;                 for (int e = 0; e < 4; ++e) v[e] = (j < 4) ? v[e] * cq[e] - pt[e] * sq[e] : v[e] * cq[e] + pt[e] * sq[e];
;             }
;             u32x2 o; o.x = cvt_pk_bf16(v[0], v[1]); o.y = cvt_pk_bf16(v[2], v[3]);
;             { int w8 = __builtin_amdgcn_cvt_pk_fp8_f32(v[0], v[1], 0, false); w8 = __builtin_amdgcn_cvt_pk_fp8_f32(v[2], v[3], w8, true);
;               if (isq) *(int*)((unsigned char*)Qb + (size_t)tok * 2048 + head * 128 + 4 * j) = w8;
;               else *(int*)((unsigned char*)Kb + (size_t)tok * 512 + (head - 16) * 128 + 4 * j) = w8; }
.LBB0_756:
	s_or_b64 exec, exec, s[22:23]
	s_waitcnt lgkmcnt(1)
	v_cvt_pk_bf16_f32 v58, v56, v57
	s_nop 0
	v_cvt_pk_bf16_f32 v58, v54, v55
	s_nop 0
	v_mov_b32_e32 v58, v161
	v_cvt_pk_fp8_f32 v58, v56, v57
	v_cvt_pk_fp8_f32 v58, v54, v55 op_sel:[0,0,1]
	v_add_co_u32_e32 v54, vcc, 0x1b500000, v50
	global_store_dword v[52:53], v58, off offset:-256
	s_nop 0
	v_addc_co_u32_e32 v55, vcc, 0, v51, vcc
	global_load_dwordx2 v[54:55], v[54:55], off offset:2048
	s_waitcnt vmcnt(0)
	v_lshlrev_b32_e32 v60, 16, v54
	s_waitcnt lgkmcnt(0)
	global_load_dwordx4 v[56:59], v[16:17], off
	v_and_b32_e32 v61, 0xffff0000, v54
	v_and_b32_e32 v70, 0xffff0000, v55
	v_pk_mul_f32 v[68:69], v[60:61], v[60:61]
	v_and_b32_e32 v71, s0, v55
	v_lshlrev_b32_e32 v55, 16, v55
	v_mov_b32_e32 v54, v70
	v_pk_mul_f32 v[72:73], v[54:55], v[54:55]
	v_add_f32_e32 v68, v68, v69
	v_add_f32_e32 v68, v73, v68
	v_add_f32_e32 v68, v72, v68
	ds_bpermute_b32 v69, v64, v68
	v_pk_mov_b32 v[54:55], v[54:55], v[70:71] op_sel:[1,0]
	s_waitcnt lgkmcnt(0)
	v_add_f32_e32 v68, v68, v69
	s_nop 1
	v_add_f32_dpp v68, v68, v68 row_ror:8 row_mask:0xf bank_mask:0xf
	s_nop 1
	v_add_f32_dpp v68, v68, v68 row_ror:4 row_mask:0xf bank_mask:0xf
	s_nop 1
	v_add_f32_dpp v68, v68, v68 row_ror:2 row_mask:0xf bank_mask:0xf
	s_nop 1
	v_add_f32_dpp v68, v68, v68 row_ror:1 row_mask:0xf bank_mask:0xf
	v_fmamk_f32 v68, v68, 0x3c000000, v189
	v_cmp_gt_f32_e32 vcc, s78, v68
	v_mul_f32_e32 v69, 0x4b800000, v68
	s_nop 0
	v_cndmask_b32_e32 v68, v68, v69, vcc
	v_rsq_f32_e32 v68, v68
	s_nop 0
	v_mul_f32_e32 v69, 0x45800000, v68
	v_cndmask_b32_e32 v68, v68, v69, vcc
	v_pk_mul_f32 v[60:61], v[68:69], v[60:61] op_sel_hi:[0,1]
	v_pk_mul_f32 v[54:55], v[68:69], v[54:55] op_sel_hi:[0,1]
	s_waitcnt vmcnt(0)
	v_pk_mul_f32 v[54:55], v[58:59], v[54:55]
	v_pk_mul_f32 v[56:57], v[56:57], v[60:61]
	ds_bpermute_b32 v60, v63, v56
	ds_bpermute_b32 v61, v63, v57
	ds_bpermute_b32 v58, v63, v54
	ds_bpermute_b32 v59, v63, v55
	s_and_saveexec_b64 s[22:23], s[8:9]
	s_cbranch_execz .LBB0_758
	s_waitcnt lgkmcnt(2)
	v_pk_mul_f32 v[60:61], v[46:47], v[60:61]
	s_waitcnt lgkmcnt(0)
	v_pk_mul_f32 v[58:59], v[48:49], v[58:59]
	v_cndmask_b32_e64 v61, v61, -v61, s[10:11]
	v_cndmask_b32_e64 v60, v60, -v60, s[10:11]
	v_cndmask_b32_e64 v59, v59, -v59, s[10:11]
	v_cndmask_b32_e64 v58, v58, -v58, s[10:11]
	v_pk_fma_f32 v[56:57], v[42:43], v[56:57], v[60:61]
	v_pk_fma_f32 v[54:55], v[44:45], v[54:55], v[58:59]
.LBB0_758:
	s_or_b64 exec, exec, s[22:23]
	s_waitcnt lgkmcnt(1)
	v_cvt_pk_bf16_f32 v58, v56, v57
	s_nop 0
	v_cvt_pk_bf16_f32 v58, v54, v55
	s_nop 0
	v_mov_b32_e32 v58, v161
	v_cvt_pk_fp8_f32 v58, v56, v57
	v_cvt_pk_fp8_f32 v58, v54, v55 op_sel:[0,0,1]
	v_add_co_u32_e32 v54, vcc, 0x1b500000, v50
	global_store_dword v[52:53], v58, off
	s_nop 0
	v_addc_co_u32_e32 v55, vcc, 0, v51, vcc
	global_load_dwordx2 v[54:55], v[54:55], off offset:2560
	s_waitcnt vmcnt(0)
	v_lshlrev_b32_e32 v60, 16, v54
	s_waitcnt lgkmcnt(0)
	global_load_dwordx4 v[56:59], v[16:17], off
	v_and_b32_e32 v61, 0xffff0000, v54
	v_and_b32_e32 v70, 0xffff0000, v55
	v_pk_mul_f32 v[68:69], v[60:61], v[60:61]
	v_and_b32_e32 v71, s0, v55
	v_lshlrev_b32_e32 v55, 16, v55
	v_mov_b32_e32 v54, v70
	v_pk_mul_f32 v[72:73], v[54:55], v[54:55]
	v_add_f32_e32 v68, v68, v69
	v_add_f32_e32 v68, v73, v68
	v_add_f32_e32 v68, v72, v68
	ds_bpermute_b32 v69, v64, v68
	v_pk_mov_b32 v[54:55], v[54:55], v[70:71] op_sel:[1,0]
	s_waitcnt lgkmcnt(0)
	v_add_f32_e32 v68, v68, v69
	s_nop 1
	v_add_f32_dpp v68, v68, v68 row_ror:8 row_mask:0xf bank_mask:0xf
	s_nop 1
	v_add_f32_dpp v68, v68, v68 row_ror:4 row_mask:0xf bank_mask:0xf
	s_nop 1
	v_add_f32_dpp v68, v68, v68 row_ror:2 row_mask:0xf bank_mask:0xf
	s_nop 1
	v_add_f32_dpp v68, v68, v68 row_ror:1 row_mask:0xf bank_mask:0xf
	v_fmamk_f32 v68, v68, 0x3c000000, v189
	v_cmp_gt_f32_e32 vcc, s78, v68
	v_mul_f32_e32 v69, 0x4b800000, v68
	s_nop 0
	v_cndmask_b32_e32 v68, v68, v69, vcc
	v_rsq_f32_e32 v68, v68
	s_nop 0
	v_mul_f32_e32 v69, 0x45800000, v68
	v_cndmask_b32_e32 v68, v68, v69, vcc
	v_pk_mul_f32 v[60:61], v[68:69], v[60:61] op_sel_hi:[0,1]
	v_pk_mul_f32 v[54:55], v[68:69], v[54:55] op_sel_hi:[0,1]
	s_waitcnt vmcnt(0)
	v_pk_mul_f32 v[54:55], v[58:59], v[54:55]
	v_pk_mul_f32 v[56:57], v[56:57], v[60:61]
	ds_bpermute_b32 v60, v63, v56
	ds_bpermute_b32 v61, v63, v57
	ds_bpermute_b32 v58, v63, v54
	ds_bpermute_b32 v59, v63, v55
	s_and_saveexec_b64 s[22:23], s[8:9]
	s_cbranch_execz .LBB0_760
	s_waitcnt lgkmcnt(2)
	v_pk_mul_f32 v[60:61], v[46:47], v[60:61]
	s_waitcnt lgkmcnt(0)
	v_pk_mul_f32 v[58:59], v[48:49], v[58:59]
	v_cndmask_b32_e64 v61, v61, -v61, s[10:11]
	v_cndmask_b32_e64 v60, v60, -v60, s[10:11]
	v_cndmask_b32_e64 v59, v59, -v59, s[10:11]
	v_cndmask_b32_e64 v58, v58, -v58, s[10:11]
	v_pk_fma_f32 v[56:57], v[42:43], v[56:57], v[60:61]
	v_pk_fma_f32 v[54:55], v[44:45], v[54:55], v[58:59]
; __device__ __forceinline__ unsigned cvt_pk_bf16(float lo, float hi) { unsigned r; asm volatile("v_cvt_pk_bf16_f32 %0, %1, %2" : "=v"(r) : "v"(lo), "v"(hi)); return r; }
; __device__ __forceinline__ float bf_lo(unsigned v) { return __uint_as_float(v << 16); }
; __device__ __forceinline__ float bf_hi(unsigned v) { return __uint_as_float(v & 0xffff0000u); }
; __device__ __forceinline__ float rinv_of(float ss, float invn) { return rsqrtf(ss * invn + 1e-6f); }
; __device__ __forceinline__ void prep_phase(const int TID, const int BID, PP p) {
;     ...
;         for (int it = 0; it < 10; ++it) {
;             const int head = 2 * it + (lane >> 5), j = lane & 31;
;             const bool isq = head < 16;
;             const int col = isq ? head * 128 : 2048 + (head - 16) * 128;
;             const u32x2 rw = *(const u32x2*)(r + col + 4 * j);
;             f32x4 v = (f32x4){bf_lo(rw.x), bf_hi(rw.x), bf_lo(rw.y), bf_hi(rw.y)};
;             float ss = v[0] * v[0] + v[1] * v[1] + v[2] * v[2] + v[3] * v[3];
; #pragma unroll
;             for (int o = 16; o > 0; o >>= 1) ss += __shfl_xor(ss, o);
;             const float rn = rinv_of(ss, 1.0f / 128.0f);
;             const f32x4 g4 = *(const f32x4*)((isq ? p->attn_q_gain : p->attn_k_gain) + 4 * j);
;             v = v * rn * g4;
;             f32x4 pt;
; #pragma unroll
;             for (int e = 0; e < 4; ++e) pt[e] = __shfl_xor(v[e], 4);
;             if (j < 8) {
; #pragma unroll
;                 for (int e = 0; e < 4; ++e) v[e] = (j < 4) ? v[e] * cq[e] - pt[e] * sq[e] : v[e] * cq[e] + pt[e] * sq[e];
;             }
;             u32x2 o; o.x = cvt_pk_bf16(v[0], v[1]); o.y = cvt_pk_bf16(v[2], v[3]);
;             { int w8 = __builtin_amdgcn_cvt_pk_fp8_f32(v[0], v[1], 0, false); w8 = __builtin_amdgcn_cvt_pk_fp8_f32(v[2], v[3], w8, true);
;               if (isq) *(int*)((unsigned char*)Qb + (size_t)tok * 2048 + head * 128 + 4 * j) = w8;
;               else *(int*)((unsigned char*)Kb + (size_t)tok * 512 + (head - 16) * 128 + 4 * j) = w8; }
.LBB0_760:
	s_or_b64 exec, exec, s[22:23]
	s_waitcnt lgkmcnt(1)
	v_cvt_pk_bf16_f32 v58, v56, v57
	s_nop 0
	v_cvt_pk_bf16_f32 v58, v54, v55
	s_nop 0
	v_mov_b32_e32 v58, v161
	v_cvt_pk_fp8_f32 v58, v56, v57
	v_cvt_pk_fp8_f32 v58, v54, v55 op_sel:[0,0,1]
	v_add_co_u32_e32 v54, vcc, 0x1b500000, v50
	global_store_dword v[52:53], v58, off offset:256
	s_nop 0
	v_addc_co_u32_e32 v55, vcc, 0, v51, vcc
	global_load_dwordx2 v[54:55], v[54:55], off offset:3072
	s_waitcnt vmcnt(0)
	v_lshlrev_b32_e32 v60, 16, v54
	s_waitcnt lgkmcnt(0)
	global_load_dwordx4 v[56:59], v[16:17], off
	v_and_b32_e32 v61, 0xffff0000, v54
	v_and_b32_e32 v70, 0xffff0000, v55
	v_pk_mul_f32 v[68:69], v[60:61], v[60:61]
	v_and_b32_e32 v71, s0, v55
	v_lshlrev_b32_e32 v55, 16, v55
	v_mov_b32_e32 v54, v70
	v_pk_mul_f32 v[72:73], v[54:55], v[54:55]
	v_add_f32_e32 v68, v68, v69
	v_add_f32_e32 v68, v73, v68
	v_add_f32_e32 v68, v72, v68
	ds_bpermute_b32 v69, v64, v68
	v_pk_mov_b32 v[54:55], v[54:55], v[70:71] op_sel:[1,0]
	s_waitcnt lgkmcnt(0)
	v_add_f32_e32 v68, v68, v69
	s_nop 1
	v_add_f32_dpp v68, v68, v68 row_ror:8 row_mask:0xf bank_mask:0xf
	s_nop 1
	v_add_f32_dpp v68, v68, v68 row_ror:4 row_mask:0xf bank_mask:0xf
	s_nop 1
	v_add_f32_dpp v68, v68, v68 row_ror:2 row_mask:0xf bank_mask:0xf
	s_nop 1
	v_add_f32_dpp v68, v68, v68 row_ror:1 row_mask:0xf bank_mask:0xf
	v_fmamk_f32 v68, v68, 0x3c000000, v189
	v_cmp_gt_f32_e32 vcc, s78, v68
	v_mul_f32_e32 v69, 0x4b800000, v68
	s_nop 0
	v_cndmask_b32_e32 v68, v68, v69, vcc
	v_rsq_f32_e32 v68, v68
	s_nop 0
	v_mul_f32_e32 v69, 0x45800000, v68
	v_cndmask_b32_e32 v68, v68, v69, vcc
	v_pk_mul_f32 v[60:61], v[68:69], v[60:61] op_sel_hi:[0,1]
	v_pk_mul_f32 v[54:55], v[68:69], v[54:55] op_sel_hi:[0,1]
	s_waitcnt vmcnt(0)
	v_pk_mul_f32 v[54:55], v[58:59], v[54:55]
	v_pk_mul_f32 v[56:57], v[56:57], v[60:61]
	ds_bpermute_b32 v60, v63, v56
	ds_bpermute_b32 v61, v63, v57
	ds_bpermute_b32 v58, v63, v54
	ds_bpermute_b32 v59, v63, v55
	s_and_saveexec_b64 s[22:23], s[8:9]
	s_cbranch_execz .LBB0_762
	s_waitcnt lgkmcnt(2)
	v_pk_mul_f32 v[60:61], v[46:47], v[60:61]
	s_waitcnt lgkmcnt(0)
	v_pk_mul_f32 v[58:59], v[48:49], v[58:59]
	v_cndmask_b32_e64 v61, v61, -v61, s[10:11]
	v_cndmask_b32_e64 v60, v60, -v60, s[10:11]
	v_cndmask_b32_e64 v59, v59, -v59, s[10:11]
	v_cndmask_b32_e64 v58, v58, -v58, s[10:11]
	v_pk_fma_f32 v[56:57], v[42:43], v[56:57], v[60:61]
	v_pk_fma_f32 v[54:55], v[44:45], v[54:55], v[58:59]
.LBB0_762:
	s_or_b64 exec, exec, s[22:23]
	s_waitcnt lgkmcnt(1)
	v_cvt_pk_bf16_f32 v58, v56, v57
	s_nop 0
	v_cvt_pk_bf16_f32 v58, v54, v55
	s_nop 0
	v_mov_b32_e32 v58, v161
	v_cvt_pk_fp8_f32 v58, v56, v57
	v_cvt_pk_fp8_f32 v58, v54, v55 op_sel:[0,0,1]
	v_add_co_u32_e32 v54, vcc, 0x1b500000, v50
	global_store_dword v[52:53], v58, off offset:512
	s_nop 0
	v_addc_co_u32_e32 v55, vcc, 0, v51, vcc
	global_load_dwordx2 v[54:55], v[54:55], off offset:3584
	s_waitcnt vmcnt(0)
	v_lshlrev_b32_e32 v60, 16, v54
	s_waitcnt lgkmcnt(0)
	global_load_dwordx4 v[56:59], v[16:17], off
	v_and_b32_e32 v61, 0xffff0000, v54
	v_and_b32_e32 v70, 0xffff0000, v55
	v_pk_mul_f32 v[68:69], v[60:61], v[60:61]
	v_and_b32_e32 v71, s0, v55
	v_lshlrev_b32_e32 v55, 16, v55
	v_mov_b32_e32 v54, v70
	v_pk_mul_f32 v[72:73], v[54:55], v[54:55]
	v_add_f32_e32 v68, v68, v69
	v_add_f32_e32 v68, v73, v68
	v_add_f32_e32 v68, v72, v68
	ds_bpermute_b32 v69, v64, v68
	v_pk_mov_b32 v[54:55], v[54:55], v[70:71] op_sel:[1,0]
	s_waitcnt lgkmcnt(0)
	v_add_f32_e32 v68, v68, v69
	s_nop 1
	v_add_f32_dpp v68, v68, v68 row_ror:8 row_mask:0xf bank_mask:0xf
	s_nop 1
	v_add_f32_dpp v68, v68, v68 row_ror:4 row_mask:0xf bank_mask:0xf
	s_nop 1
	v_add_f32_dpp v68, v68, v68 row_ror:2 row_mask:0xf bank_mask:0xf
	s_nop 1
	v_add_f32_dpp v68, v68, v68 row_ror:1 row_mask:0xf bank_mask:0xf
	v_fmamk_f32 v68, v68, 0x3c000000, v189
	v_cmp_gt_f32_e32 vcc, s78, v68
	v_mul_f32_e32 v69, 0x4b800000, v68
	s_nop 0
	v_cndmask_b32_e32 v68, v68, v69, vcc
	v_rsq_f32_e32 v68, v68
	s_nop 0
	v_mul_f32_e32 v69, 0x45800000, v68
	v_cndmask_b32_e32 v68, v68, v69, vcc
	v_pk_mul_f32 v[60:61], v[68:69], v[60:61] op_sel_hi:[0,1]
	v_pk_mul_f32 v[54:55], v[68:69], v[54:55] op_sel_hi:[0,1]
	s_waitcnt vmcnt(0)
	v_pk_mul_f32 v[54:55], v[58:59], v[54:55]
	v_pk_mul_f32 v[56:57], v[56:57], v[60:61]
	ds_bpermute_b32 v60, v63, v56
	ds_bpermute_b32 v61, v63, v57
	ds_bpermute_b32 v58, v63, v54
	ds_bpermute_b32 v59, v63, v55
	s_and_saveexec_b64 s[22:23], s[8:9]
	s_cbranch_execz .LBB0_764
	s_waitcnt lgkmcnt(2)
	v_pk_mul_f32 v[60:61], v[46:47], v[60:61]
	s_waitcnt lgkmcnt(0)
	v_pk_mul_f32 v[58:59], v[48:49], v[58:59]
	v_cndmask_b32_e64 v61, v61, -v61, s[10:11]
	v_cndmask_b32_e64 v60, v60, -v60, s[10:11]
	v_cndmask_b32_e64 v59, v59, -v59, s[10:11]
	v_cndmask_b32_e64 v58, v58, -v58, s[10:11]
	v_pk_fma_f32 v[56:57], v[42:43], v[56:57], v[60:61]
	v_pk_fma_f32 v[54:55], v[44:45], v[54:55], v[58:59]
; __device__ __forceinline__ unsigned cvt_pk_bf16(float lo, float hi) { unsigned r; asm volatile("v_cvt_pk_bf16_f32 %0, %1, %2" : "=v"(r) : "v"(lo), "v"(hi)); return r; }
; __device__ __forceinline__ float bf_lo(unsigned v) { return __uint_as_float(v << 16); }
; __device__ __forceinline__ float bf_hi(unsigned v) { return __uint_as_float(v & 0xffff0000u); }
; __device__ __forceinline__ float rinv_of(float ss, float invn) { return rsqrtf(ss * invn + 1e-6f); }
; __device__ __forceinline__ void prep_phase(const int TID, const int BID, PP p) {
;     ...
;         for (int it = 0; it < 10; ++it) {
;             const int head = 2 * it + (lane >> 5), j = lane & 31;
;             const bool isq = head < 16;
;             const int col = isq ? head * 128 : 2048 + (head - 16) * 128;
;             const u32x2 rw = *(const u32x2*)(r + col + 4 * j);
;             f32x4 v = (f32x4){bf_lo(rw.x), bf_hi(rw.x), bf_lo(rw.y), bf_hi(rw.y)};
;             float ss = v[0] * v[0] + v[1] * v[1] + v[2] * v[2] + v[3] * v[3];
; #pragma unroll
;             for (int o = 16; o > 0; o >>= 1) ss += __shfl_xor(ss, o);
;             const float rn = rinv_of(ss, 1.0f / 128.0f);
;             const f32x4 g4 = *(const f32x4*)((isq ? p->attn_q_gain : p->attn_k_gain) + 4 * j);
;             v = v * rn * g4;
;             f32x4 pt;
; #pragma unroll
;             for (int e = 0; e < 4; ++e) pt[e] = __shfl_xor(v[e], 4);
;             if (j < 8) {
; #pragma unroll
;                 for (int e = 0; e < 4; ++e) v[e] = (j < 4) ? v[e] * cq[e] - pt[e] * sq[e] : v[e] * cq[e] + pt[e] * sq[e];
;             }
;             u32x2 o; o.x = cvt_pk_bf16(v[0], v[1]); o.y = cvt_pk_bf16(v[2], v[3]);
;             { int w8 = __builtin_amdgcn_cvt_pk_fp8_f32(v[0], v[1], 0, false); w8 = __builtin_amdgcn_cvt_pk_fp8_f32(v[2], v[3], w8, true);
;               if (isq) *(int*)((unsigned char*)Qb + (size_t)tok * 2048 + head * 128 + 4 * j) = w8;
;               else *(int*)((unsigned char*)Kb + (size_t)tok * 512 + (head - 16) * 128 + 4 * j) = w8; }
.LBB0_764:
	s_or_b64 exec, exec, s[22:23]
	s_waitcnt lgkmcnt(1)
	v_cvt_pk_bf16_f32 v58, v56, v57
	s_nop 0
	v_cvt_pk_bf16_f32 v58, v54, v55
	s_nop 0
	v_mov_b32_e32 v58, v161
	v_cvt_pk_fp8_f32 v58, v56, v57
	v_cvt_pk_fp8_f32 v58, v54, v55 op_sel:[0,0,1]
	global_store_dword v[52:53], v58, off offset:768
	v_add_co_u32_e32 v52, vcc, 0x1b501000, v50
	s_nop 1
	v_addc_co_u32_e32 v53, vcc, 0, v51, vcc
	global_load_dwordx2 v[54:55], v[52:53], off
	s_waitcnt vmcnt(0)
	v_lshlrev_b32_e32 v58, 16, v54
	s_waitcnt lgkmcnt(0)
	v_and_b32_e32 v59, 0xffff0000, v54
	v_and_b32_e32 v52, 0xffff0000, v55
	v_pk_mul_f32 v[56:57], v[58:59], v[58:59]
	v_lshlrev_b32_e32 v61, 16, v55
	v_mov_b32_e32 v60, v52
	v_and_b32_e32 v53, s0, v55
	v_pk_mul_f32 v[54:55], v[60:61], v[60:61]
	v_add_f32_e32 v56, v56, v57
	v_add_f32_e32 v55, v55, v56
	v_add_f32_e32 v54, v54, v55
	ds_bpermute_b32 v55, v64, v54
	v_readlane_b32 s0, v254, 32
	v_readlane_b32 s1, v254, 33
	s_load_dwordx2 s[22:23], s[0:1], 0x38
	v_pk_mov_b32 v[52:53], v[60:61], v[52:53] op_sel:[1,0]
	s_waitcnt lgkmcnt(0)
	v_add_f32_e32 v54, v54, v55
	s_nop 1
	v_add_f32_dpp v54, v54, v54 row_ror:8 row_mask:0xf bank_mask:0xf
	s_nop 1
	v_add_f32_dpp v54, v54, v54 row_ror:4 row_mask:0xf bank_mask:0xf
	s_nop 1
	v_add_f32_dpp v54, v54, v54 row_ror:2 row_mask:0xf bank_mask:0xf
	s_nop 1
	v_add_f32_dpp v54, v54, v54 row_ror:1 row_mask:0xf bank_mask:0xf
	v_fmamk_f32 v54, v54, 0x3c000000, v189
	v_cmp_gt_f32_e32 vcc, s78, v54
	v_mul_f32_e32 v55, 0x4b800000, v54
	s_nop 0
	v_cndmask_b32_e32 v54, v54, v55, vcc
	v_rsq_f32_e32 v54, v54
	s_nop 0
	v_mul_f32_e32 v55, 0x45800000, v54
	v_cndmask_b32_e32 v68, v54, v55, vcc
	global_load_dwordx4 v[54:57], v160, s[22:23]
	v_pk_mul_f32 v[58:59], v[68:69], v[58:59] op_sel_hi:[0,1]
	v_pk_mul_f32 v[52:53], v[68:69], v[52:53] op_sel_hi:[0,1]
	s_waitcnt vmcnt(0)
	v_pk_mul_f32 v[52:53], v[56:57], v[52:53]
	v_pk_mul_f32 v[54:55], v[54:55], v[58:59]
	ds_bpermute_b32 v58, v63, v54
	ds_bpermute_b32 v59, v63, v55
	ds_bpermute_b32 v56, v63, v52
	ds_bpermute_b32 v57, v63, v53
	s_and_saveexec_b64 s[24:25], s[8:9]
	s_cbranch_execz .LBB0_766
	s_waitcnt lgkmcnt(2)
	v_pk_mul_f32 v[58:59], v[46:47], v[58:59]
	s_waitcnt lgkmcnt(0)
	v_pk_mul_f32 v[56:57], v[48:49], v[56:57]
	v_cndmask_b32_e64 v59, v59, -v59, s[10:11]
	v_cndmask_b32_e64 v58, v58, -v58, s[10:11]
	v_cndmask_b32_e64 v57, v57, -v57, s[10:11]
	v_cndmask_b32_e64 v56, v56, -v56, s[10:11]
	v_pk_fma_f32 v[54:55], v[42:43], v[54:55], v[58:59]
	v_pk_fma_f32 v[52:53], v[44:45], v[52:53], v[56:57]
.LBB0_766:
	s_or_b64 exec, exec, s[24:25]
	s_waitcnt lgkmcnt(3)
	v_cvt_pk_bf16_f32 v58, v54, v55
	s_mov_b32 s0, 0x1b501000
	v_cvt_pk_bf16_f32 v58, v52, v53
	s_waitcnt lgkmcnt(0)
	v_lshl_add_u64 v[56:57], s[22:23], 0, v[160:161]
	v_mov_b32_e32 v58, v161
	v_cvt_pk_fp8_f32 v58, v54, v55
	v_cvt_pk_fp8_f32 v58, v52, v53 op_sel:[0,0,1]
	v_lshl_add_u64 v[52:53], s[2:3], 0, v[34:35]
	v_add_co_u32_e32 v52, vcc, s63, v52
	s_nop 1
	v_addc_co_u32_e32 v53, vcc, 0, v53, vcc
	v_add_co_u32_e32 v50, vcc, s0, v50
	global_store_dword v[52:53], v58, off
	s_nop 0
	v_addc_co_u32_e32 v51, vcc, 0, v51, vcc
	global_load_dwordx2 v[50:51], v[50:51], off offset:512
	s_waitcnt vmcnt(0)
	v_lshlrev_b32_e32 v58, 16, v50
	global_load_dwordx4 v[54:57], v[56:57], off
	v_and_b32_e32 v59, 0xffff0000, v50
	v_and_b32_e32 v68, 0xffff0000, v51
	v_pk_mul_f32 v[60:61], v[58:59], v[58:59]
	v_and_b32_e32 v69, s0, v51
	v_lshlrev_b32_e32 v51, 16, v51
	v_mov_b32_e32 v50, v68
	v_pk_mul_f32 v[70:71], v[50:51], v[50:51]
	v_add_f32_e32 v60, v60, v61
	v_add_f32_e32 v60, v71, v60
	v_add_f32_e32 v60, v70, v60
	ds_bpermute_b32 v61, v64, v60
	v_pk_mov_b32 v[50:51], v[50:51], v[68:69] op_sel:[1,0]
	s_waitcnt lgkmcnt(0)
	v_add_f32_e32 v60, v60, v61
	s_nop 1
	v_add_f32_dpp v60, v60, v60 row_ror:8 row_mask:0xf bank_mask:0xf
	s_nop 1
	v_add_f32_dpp v60, v60, v60 row_ror:4 row_mask:0xf bank_mask:0xf
	s_nop 1
	v_add_f32_dpp v60, v60, v60 row_ror:2 row_mask:0xf bank_mask:0xf
	s_nop 1
	v_add_f32_dpp v60, v60, v60 row_ror:1 row_mask:0xf bank_mask:0xf
	v_fmamk_f32 v60, v60, 0x3c000000, v189
	v_cmp_gt_f32_e32 vcc, s78, v60
	v_mul_f32_e32 v61, 0x4b800000, v60
	s_nop 0
	v_cndmask_b32_e32 v60, v60, v61, vcc
	v_rsq_f32_e32 v60, v60
	s_nop 0
	v_mul_f32_e32 v61, 0x45800000, v60
	v_cndmask_b32_e32 v60, v60, v61, vcc
	v_pk_mul_f32 v[58:59], v[60:61], v[58:59] op_sel_hi:[0,1]
	v_pk_mul_f32 v[50:51], v[60:61], v[50:51] op_sel_hi:[0,1]
	s_waitcnt vmcnt(0)
	v_pk_mul_f32 v[50:51], v[56:57], v[50:51]
	v_pk_mul_f32 v[54:55], v[54:55], v[58:59]
	ds_bpermute_b32 v58, v63, v54
	ds_bpermute_b32 v59, v63, v55
	ds_bpermute_b32 v56, v63, v50
	ds_bpermute_b32 v57, v63, v51
	s_and_saveexec_b64 s[22:23], s[8:9]
	s_cbranch_execz .LBB0_768
	s_waitcnt lgkmcnt(2)
	v_pk_mul_f32 v[46:47], v[46:47], v[58:59]
	s_nop 0
	v_cndmask_b32_e64 v47, v47, -v47, s[10:11]
	v_cndmask_b32_e64 v46, v46, -v46, s[10:11]
	v_pk_fma_f32 v[54:55], v[42:43], v[54:55], v[46:47]
	s_waitcnt lgkmcnt(0)
	v_pk_mul_f32 v[42:43], v[48:49], v[56:57]
	s_nop 0
	v_cndmask_b32_e64 v43, v43, -v43, s[10:11]
	v_cndmask_b32_e64 v42, v42, -v42, s[10:11]
	v_pk_fma_f32 v[50:51], v[44:45], v[50:51], v[42:43]
